# in-loop plain epilogue: row-scale (ssq -> rsqrt) computation hoisted from the store-carrying last load segment into the previous load segment of the same K-step
# baseline (speedup 1.0000x reference)
; #define PG8_STAGE(bufoff, gbase, voff) do { _Pragma("unroll") for (int _i = 0; _i < 2; ++_i) \
;         __builtin_amdgcn_global_load_lds((const unsigned*)((const char*)(gbase) + (voff)[_i]), (LAS unsigned*)(lds + (bufoff) + ldsw + _i * 8192), 16, 0, 0); } while (0)
; #define PG8_LDA(dst, b, h) do { _Pragma("unroll") for (int m = 0; m < 4; ++m) _Pragma("unroll") for (int k = 0; k < 2; ++k) dst[m][k] = *(const LAS bf16x8*)(lds + PG8_SA(b, h) + aoff + m * 2048 + k * 1024); } while (0)
; #define PG8_LDB(dst, b, h) do { _Pragma("unroll") for (int n = 0; n < 2; ++n) _Pragma("unroll") for (int k = 0; k < 2; ++k) dst[n][k] = *(const LAS bf16x8*)(lds + PG8_SB(b, h) + boff + n * 2048 + k * 1024); } while (0)
; #define PG8_MMA(ai, bj, At, Bt) do { __builtin_amdgcn_s_setprio(1); _Pragma("unroll") for (int m = 0; m < 4; ++m) _Pragma("unroll") for (int n = 0; n < 2; ++n) _Pragma("unroll") for (int k = 0; k < 2; ++k) \
;         acc[ai][bj][m][n] = __builtin_amdgcn_mfma_f32_16x16x32_bf16(Bt[n][k], At[m][k], acc[ai][bj][m][n], 0, 0, 0); __builtin_amdgcn_s_setprio(0); } while (0)
; #define PG8_WAIT_V(n) asm volatile("s_waitcnt vmcnt(" #n ")" ::: "memory")
; #define PG8_WAIT_L(n) asm volatile("s_waitcnt lgkmcnt(" #n ")" ::: "memory")
; #define PG8_BAR __builtin_amdgcn_s_barrier()
; #define PG8_SCHED __builtin_amdgcn_sched_barrier(0)
; template <class Epi>
; __device__ __forceinline__ void gemm_phase(LAS unsigned char* lds, const Gemm g, const StaticOrder& S, const Epi& E) {
;     ...
;             PG8_LDB(B0, 0, 0); PG8_SCHED; PG8_LDA(At, 0, 0); PG8_STAGE(PG8_SA(1, 1), a1 + hstepA, voffA);
;             PG8_WAIT_L(8); PG8_BAR; PG8_WAIT_L(0); PG8_MMA(0, 0, At, B0); PG8_BAR; PG8_SCHED;
;             PG8_LDB(B1, 0, 1); PG8_STAGE(PG8_SB(0, 0), b2, voffB);
;             PG8_BAR; PG8_WAIT_L(0); PG8_MMA(0, 1, At, B1); PG8_BAR;
;             PG8_LDA(At, 0, 1); PG8_STAGE(PG8_SA(0, 0), a2, voffA);
;             PG8_BAR; PG8_WAIT_L(0); PG8_MMA(1, 0, At, B0); PG8_BAR; PG8_SCHED;
;             PG8_STAGE(PG8_SB(0, 1), b2 + hstepB, voffB);
;             PG8_WAIT_V(6); PG8_BAR; PG8_MMA(1, 1, At, B1); PG8_BAR;
.LBB0_116:
	s_add_i32 s35, s44, 2
	s_add_u32 s46, s36, 0x80
	s_addc_u32 s45, s37, 0
	s_cmp_eq_u32 s17, s44
	s_cselect_b32 s45, s29, s45
	s_cselect_b32 s44, s28, s46
	s_cselect_b32 s47, s31, s70
	s_cselect_b32 s46, s30, s69
	v_lshl_add_u64 v[166:167], s[36:37], 0, v[186:187]
	s_add_i32 m0, s39, 0xc000
	ds_read_b128 v[146:149], v228
	ds_read_b128 v[150:153], v228 offset:1024
	ds_read_b128 v[154:157], v228 offset:2048
	ds_read_b128 v[158:161], v228 offset:3072
	ds_read_b128 v[162:165], v228 offset:4096
	ds_read_b128 v[190:193], v228 offset:5120
	ds_read_b128 v[194:197], v228 offset:6144
	ds_read_b128 v[198:201], v228 offset:7168
	global_load_lds_dwordx4 v[166:167], off
	v_lshl_add_u64 v[166:167], s[36:37], 0, v[188:189]
	s_add_i32 m0, s39, 0xe000
	v_add_u32_e32 v142, 0x10000, v225
	global_load_lds_dwordx4 v[166:167], off
	ds_read_b128 v[130:133], v142
	ds_read_b128 v[134:137], v142 offset:1024
	ds_read_b128 v[138:141], v142 offset:2048
	ds_read_b128 v[142:145], v142 offset:3072
	v_add_u32_e32 v166, 0x14000, v225
	ds_read_b128 v[202:205], v166
	ds_read_b128 v[230:233], v166 offset:1024
	ds_read_b128 v[234:237], v166 offset:2048
	ds_read_b128 v[238:241], v166 offset:3072
	s_waitcnt vmcnt(8) lgkmcnt(0)
	s_barrier
	v_mfma_f32_16x16x32_bf16 v[124:127], v[130:133], v[146:149], v[124:127]
	v_mfma_f32_16x16x32_bf16 v[120:123], v[138:141], v[146:149], v[120:123]
	v_mfma_f32_16x16x32_bf16 v[112:115], v[130:133], v[154:157], v[112:115]
	v_mfma_f32_16x16x32_bf16 v[104:107], v[138:141], v[154:157], v[104:107]
	v_mfma_f32_16x16x32_bf16 v[96:99], v[130:133], v[162:165], v[96:99]
	v_mfma_f32_16x16x32_bf16 v[88:91], v[138:141], v[162:165], v[88:91]
	v_mfma_f32_16x16x32_bf16 v[80:83], v[130:133], v[194:197], v[80:83]
	v_mfma_f32_16x16x32_bf16 v[72:75], v[138:141], v[194:197], v[72:75]
	v_mfma_f32_16x16x32_bf16 v[124:127], v[134:137], v[150:153], v[124:127]
	v_mfma_f32_16x16x32_bf16 v[120:123], v[142:145], v[150:153], v[120:123]
	v_mfma_f32_16x16x32_bf16 v[112:115], v[134:137], v[158:161], v[112:115]
	v_mfma_f32_16x16x32_bf16 v[104:107], v[142:145], v[158:161], v[104:107]
	v_mfma_f32_16x16x32_bf16 v[96:99], v[134:137], v[190:193], v[96:99]
	v_mfma_f32_16x16x32_bf16 v[88:91], v[142:145], v[190:193], v[88:91]
	v_mfma_f32_16x16x32_bf16 v[80:83], v[134:137], v[198:201], v[80:83]
	v_mfma_f32_16x16x32_bf16 v[72:75], v[142:145], v[198:201], v[72:75]
	v_mfma_f32_16x16x32_bf16 v[116:119], v[202:205], v[146:149], v[116:119]
	v_mfma_f32_16x16x32_bf16 v[108:111], v[234:237], v[146:149], v[108:111]
	v_mfma_f32_16x16x32_bf16 v[100:103], v[202:205], v[154:157], v[100:103]
	v_mfma_f32_16x16x32_bf16 v[92:95], v[234:237], v[154:157], v[92:95]
	v_mfma_f32_16x16x32_bf16 v[84:87], v[202:205], v[162:165], v[84:87]
	v_mfma_f32_16x16x32_bf16 v[76:79], v[234:237], v[162:165], v[76:79]
	v_mfma_f32_16x16x32_bf16 v[68:71], v[202:205], v[194:197], v[68:71]
	v_mfma_f32_16x16x32_bf16 v[64:67], v[234:237], v[194:197], v[64:67]
	v_mfma_f32_16x16x32_bf16 v[116:119], v[230:233], v[150:153], v[116:119]
	v_mfma_f32_16x16x32_bf16 v[108:111], v[238:241], v[150:153], v[108:111]
	v_mfma_f32_16x16x32_bf16 v[100:103], v[230:233], v[158:161], v[100:103]
	v_mfma_f32_16x16x32_bf16 v[92:95], v[238:241], v[158:161], v[92:95]
	v_mfma_f32_16x16x32_bf16 v[84:87], v[230:233], v[190:193], v[84:87]
	v_mfma_f32_16x16x32_bf16 v[76:79], v[238:241], v[190:193], v[76:79]
	v_mfma_f32_16x16x32_bf16 v[68:71], v[230:233], v[198:201], v[68:71]
	v_mfma_f32_16x16x32_bf16 v[64:67], v[238:241], v[198:201], v[64:67]
	s_barrier
	ds_read_b128 v[146:149], v228 offset:16384
	ds_read_b128 v[150:153], v228 offset:17408
	ds_read_b128 v[154:157], v228 offset:18432
	ds_read_b128 v[158:161], v228 offset:19456
	ds_read_b128 v[162:165], v228 offset:20480
	ds_read_b128 v[190:193], v228 offset:21504
	ds_read_b128 v[194:197], v228 offset:22528
	ds_read_b128 v[198:201], v228 offset:23552
	s_add_i32 s71, s57, 0x10000
	v_lshl_add_u64 v[166:167], s[46:47], 0, v[168:169]
	s_mov_b32 m0, s71
	v_lshl_add_u64 v[206:207], s[46:47], 0, v[178:179]
	global_load_lds_dwordx4 v[166:167], off
	s_add_i32 m0, s71, 0x2000
	v_lshl_add_u64 v[242:243], s[44:45], 0, v[174:175]
	global_load_lds_dwordx4 v[206:207], off
	s_mov_b32 m0, s39
	v_lshl_add_u64 v[244:245], s[44:45], 0, v[176:177]
	global_load_lds_dwordx4 v[242:243], off
	s_mov_b32 m0, s54
	s_add_u32 s46, s46, s50
	s_addc_u32 s47, s47, 0
	global_load_lds_dwordx4 v[244:245], off
	s_add_i32 s71, s57, 0x14000
	v_lshl_add_u64 v[246:247], s[46:47], 0, v[168:169]
	s_mov_b32 m0, s71
	v_lshl_add_u64 v[248:249], s[46:47], 0, v[178:179]
	global_load_lds_dwordx4 v[246:247], off
	s_add_i32 m0, s71, 0x2000
	s_nop 0
	global_load_lds_dwordx4 v[248:249], off
	s_waitcnt vmcnt(8) lgkmcnt(0)
	s_barrier
; #define PG8_STAGE(bufoff, gbase, voff) do { _Pragma("unroll") for (int _i = 0; _i < 2; ++_i) \
;         __builtin_amdgcn_global_load_lds((const unsigned*)((const char*)(gbase) + (voff)[_i]), (LAS unsigned*)(lds + (bufoff) + ldsw + _i * 8192), 16, 0, 0); } while (0)
; #define PG8_LDA(dst, b, h) do { _Pragma("unroll") for (int m = 0; m < 4; ++m) _Pragma("unroll") for (int k = 0; k < 2; ++k) dst[m][k] = *(const LAS bf16x8*)(lds + PG8_SA(b, h) + aoff + m * 2048 + k * 1024); } while (0)
; #define PG8_LDB(dst, b, h) do { _Pragma("unroll") for (int n = 0; n < 2; ++n) _Pragma("unroll") for (int k = 0; k < 2; ++k) dst[n][k] = *(const LAS bf16x8*)(lds + PG8_SB(b, h) + boff + n * 2048 + k * 1024); } while (0)
; #define PG8_MMA(ai, bj, At, Bt) do { __builtin_amdgcn_s_setprio(1); _Pragma("unroll") for (int m = 0; m < 4; ++m) _Pragma("unroll") for (int n = 0; n < 2; ++n) _Pragma("unroll") for (int k = 0; k < 2; ++k) \
;         acc[ai][bj][m][n] = __builtin_amdgcn_mfma_f32_16x16x32_bf16(Bt[n][k], At[m][k], acc[ai][bj][m][n], 0, 0, 0); __builtin_amdgcn_s_setprio(0); } while (0)
; #define PG8_WAIT_V(n) asm volatile("s_waitcnt vmcnt(" #n ")" ::: "memory")
; #define PG8_WAIT_L(n) asm volatile("s_waitcnt lgkmcnt(" #n ")" ::: "memory")
; #define PG8_BAR __builtin_amdgcn_s_barrier()
; #define PG8_SCHED __builtin_amdgcn_sched_barrier(0)
; template <class Epi>
; __device__ __forceinline__ void gemm_phase(LAS unsigned char* lds, const Gemm g, const StaticOrder& S, const Epi& E) {
;     ...
;             PG8_BAR; PG8_WAIT_L(0); PG8_MMA(1, 0, At, B0); PG8_BAR; PG8_SCHED;
;             PG8_STAGE(PG8_SB(0, 1), b2 + hstepB, voffB);
;             PG8_WAIT_V(6); PG8_BAR; PG8_MMA(1, 1, At, B1); PG8_BAR;
;             PG8_LDB(B0, 1, 0); PG8_SCHED; PG8_LDA(At, 1, 0); PG8_STAGE(PG8_SA(0, 1), a2 + hstepA, voffA);
;             PG8_WAIT_L(8); PG8_BAR; PG8_WAIT_L(0); PG8_MMA(0, 0, At, B0); PG8_BAR; PG8_SCHED;
;             PG8_LDB(B1, 1, 1); PG8_STAGE(PG8_SB(1, 0), b3, voffB);
;             PG8_BAR; PG8_WAIT_L(0); PG8_MMA(0, 1, At, B1); PG8_BAR;
;             PG8_LDA(At, 1, 1); PG8_STAGE(PG8_SA(1, 0), a3, voffA);
;     __device__ __forceinline__ void operator()(const f32x4 (&acc)[2][2][4][2], const Unit& u, int wr, int wc, int fr, int fq, const LAS float* rsl) const {
;     ...
;                 const float rstd = rsqrtf(rs[ai][m] * (1.f / 1024.f) + EPS);
	v_mfma_f32_16x16x32_bf16 v[60:63], v[130:133], v[146:149], v[60:63]
	v_mfma_f32_16x16x32_bf16 v[56:59], v[138:141], v[146:149], v[56:59]
	v_mfma_f32_16x16x32_bf16 v[52:55], v[130:133], v[154:157], v[52:55]
	v_mfma_f32_16x16x32_bf16 v[44:47], v[138:141], v[154:157], v[44:47]
	v_mfma_f32_16x16x32_bf16 v[36:39], v[130:133], v[162:165], v[36:39]
	v_mfma_f32_16x16x32_bf16 v[28:31], v[138:141], v[162:165], v[28:31]
	v_mfma_f32_16x16x32_bf16 v[20:23], v[130:133], v[194:197], v[20:23]
	v_mfma_f32_16x16x32_bf16 v[12:15], v[138:141], v[194:197], v[12:15]
	v_mfma_f32_16x16x32_bf16 v[60:63], v[134:137], v[150:153], v[60:63]
	v_mfma_f32_16x16x32_bf16 v[56:59], v[142:145], v[150:153], v[56:59]
	v_mfma_f32_16x16x32_bf16 v[52:55], v[134:137], v[158:161], v[52:55]
	v_mfma_f32_16x16x32_bf16 v[44:47], v[142:145], v[158:161], v[44:47]
	v_mfma_f32_16x16x32_bf16 v[36:39], v[134:137], v[190:193], v[36:39]
	v_mfma_f32_16x16x32_bf16 v[28:31], v[142:145], v[190:193], v[28:31]
	v_mfma_f32_16x16x32_bf16 v[20:23], v[134:137], v[198:201], v[20:23]
	v_mfma_f32_16x16x32_bf16 v[12:15], v[142:145], v[198:201], v[12:15]
	v_mfma_f32_16x16x32_bf16 v[48:51], v[202:205], v[146:149], v[48:51]
	v_mfma_f32_16x16x32_bf16 v[40:43], v[234:237], v[146:149], v[40:43]
	v_mfma_f32_16x16x32_bf16 v[32:35], v[202:205], v[154:157], v[32:35]
	v_mfma_f32_16x16x32_bf16 v[24:27], v[234:237], v[154:157], v[24:27]
	v_mfma_f32_16x16x32_bf16 v[16:19], v[202:205], v[162:165], v[16:19]
	v_mfma_f32_16x16x32_bf16 v[8:11], v[234:237], v[162:165], v[8:11]
	v_mfma_f32_16x16x32_bf16 v[4:7], v[202:205], v[194:197], v[4:7]
	v_mfma_f32_16x16x32_bf16 v[0:3], v[234:237], v[194:197], v[0:3]
	v_mfma_f32_16x16x32_bf16 v[48:51], v[230:233], v[150:153], v[48:51]
	v_mfma_f32_16x16x32_bf16 v[40:43], v[238:241], v[150:153], v[40:43]
	v_mfma_f32_16x16x32_bf16 v[32:35], v[230:233], v[158:161], v[32:35]
	v_mfma_f32_16x16x32_bf16 v[24:27], v[238:241], v[158:161], v[24:27]
	v_mfma_f32_16x16x32_bf16 v[16:19], v[230:233], v[190:193], v[16:19]
	v_mfma_f32_16x16x32_bf16 v[8:11], v[238:241], v[190:193], v[8:11]
	v_mfma_f32_16x16x32_bf16 v[4:7], v[230:233], v[198:201], v[4:7]
	v_mfma_f32_16x16x32_bf16 v[0:3], v[238:241], v[198:201], v[0:3]
	s_barrier
	s_add_u32 s44, s44, s74
	s_addc_u32 s45, s45, 0
	s_mov_b32 m0, s55
	v_lshl_add_u64 v[250:251], s[44:45], 0, v[174:175]
	ds_read_b128 v[146:149], v228 offset:32768
	ds_read_b128 v[150:153], v228 offset:33792
	ds_read_b128 v[154:157], v228 offset:34816
	ds_read_b128 v[158:161], v228 offset:35840
	ds_read_b128 v[162:165], v228 offset:36864
	ds_read_b128 v[190:193], v228 offset:37888
	ds_read_b128 v[194:197], v228 offset:38912
	ds_read_b128 v[198:201], v228 offset:39936
	global_load_lds_dwordx4 v[250:251], off
	v_lshl_add_u64 v[250:251], s[44:45], 0, v[176:177]
	s_mov_b32 m0, s3
	v_add_u32_e32 v142, 0x18000, v225
	global_load_lds_dwordx4 v[250:251], off
	ds_read_b128 v[130:133], v142
	ds_read_b128 v[134:137], v142 offset:1024
	ds_read_b128 v[138:141], v142 offset:2048
	ds_read_b128 v[142:145], v142 offset:3072
	v_add_u32_e32 v172, 0x1c000, v225
	ds_read_b128 v[202:205], v172
	ds_read_b128 v[230:233], v172 offset:1024
	ds_read_b128 v[234:237], v172 offset:2048
	ds_read_b128 v[238:241], v172 offset:3072
	s_cmp_lt_u32 s35, s16
	s_cbranch_scc1 .Lrs_skip
	s_cmp_lg_u32 s32, 1
	s_cbranch_scc1 .Lrs_skip
	v_lshl_add_u32 v172, s20, 2, v226
	ds_read2_b32 v[250:251], v172 offset1:16
	ds_read2_b32 v[252:253], v172 offset0:32 offset1:48
	s_waitcnt lgkmcnt(0)
	v_fmamk_f32 v172, v250, 0x3a800000, v209
	v_mul_f32_e32 v173, 0x4b800000, v172
	v_cmp_gt_f32_e32 vcc, s81, v172
	s_nop 1
	v_cndmask_b32_e32 v172, v172, v173, vcc
	v_rsq_f32_e32 v172, v172
	s_nop 0
	v_mul_f32_e32 v173, 0x45800000, v172
	v_cndmask_b32_e32 v250, v172, v173, vcc
	v_fmamk_f32 v172, v251, 0x3a800000, v209
	v_mul_f32_e32 v173, 0x4b800000, v172
	v_cmp_gt_f32_e32 vcc, s81, v172
	s_nop 1
	v_cndmask_b32_e32 v172, v172, v173, vcc
	v_rsq_f32_e32 v172, v172
	s_nop 0
	v_mul_f32_e32 v173, 0x45800000, v172
	v_cndmask_b32_e32 v251, v172, v173, vcc
	v_fmamk_f32 v172, v252, 0x3a800000, v209
	v_mul_f32_e32 v173, 0x4b800000, v172
	v_cmp_gt_f32_e32 vcc, s81, v172
	s_nop 1
	v_cndmask_b32_e32 v172, v172, v173, vcc
	v_rsq_f32_e32 v172, v172
	s_nop 0
	v_mul_f32_e32 v173, 0x45800000, v172
	v_cndmask_b32_e32 v252, v172, v173, vcc
	v_fmamk_f32 v172, v253, 0x3a800000, v209
	v_mul_f32_e32 v173, 0x4b800000, v172
	v_cmp_gt_f32_e32 vcc, s81, v172
	s_nop 1
	v_cndmask_b32_e32 v172, v172, v173, vcc
	v_rsq_f32_e32 v172, v172
	s_nop 0
	v_mul_f32_e32 v173, 0x45800000, v172
	v_cndmask_b32_e32 v253, v172, v173, vcc
; #define PG8_STAGE(bufoff, gbase, voff) do { _Pragma("unroll") for (int _i = 0; _i < 2; ++_i) \
;         __builtin_amdgcn_global_load_lds((const unsigned*)((const char*)(gbase) + (voff)[_i]), (LAS unsigned*)(lds + (bufoff) + ldsw + _i * 8192), 16, 0, 0); } while (0)
; #define PG8_LDA(dst, b, h) do { _Pragma("unroll") for (int m = 0; m < 4; ++m) _Pragma("unroll") for (int k = 0; k < 2; ++k) dst[m][k] = *(const LAS bf16x8*)(lds + PG8_SA(b, h) + aoff + m * 2048 + k * 1024); } while (0)
; #define PG8_LDB(dst, b, h) do { _Pragma("unroll") for (int n = 0; n < 2; ++n) _Pragma("unroll") for (int k = 0; k < 2; ++k) dst[n][k] = *(const LAS bf16x8*)(lds + PG8_SB(b, h) + boff + n * 2048 + k * 1024); } while (0)
; #define PG8_MMA(ai, bj, At, Bt) do { __builtin_amdgcn_s_setprio(1); _Pragma("unroll") for (int m = 0; m < 4; ++m) _Pragma("unroll") for (int n = 0; n < 2; ++n) _Pragma("unroll") for (int k = 0; k < 2; ++k) \
;         acc[ai][bj][m][n] = __builtin_amdgcn_mfma_f32_16x16x32_bf16(Bt[n][k], At[m][k], acc[ai][bj][m][n], 0, 0, 0); __builtin_amdgcn_s_setprio(0); } while (0)
; #define PG8_WAIT_L(n) asm volatile("s_waitcnt lgkmcnt(" #n ")" ::: "memory")
; #define PG8_BAR __builtin_amdgcn_s_barrier()
; #define PG8_SCHED __builtin_amdgcn_sched_barrier(0)
; template <class Epi>
; __device__ __forceinline__ void gemm_phase(LAS unsigned char* lds, const Gemm g, const StaticOrder& S, const Epi& E) {
;     ...
;             PG8_WAIT_L(8); PG8_BAR; PG8_WAIT_L(0); PG8_MMA(0, 0, At, B0); PG8_BAR; PG8_SCHED;
;             PG8_LDB(B1, 1, 1); PG8_STAGE(PG8_SB(1, 0), b3, voffB);
;             PG8_BAR; PG8_WAIT_L(0); PG8_MMA(0, 1, At, B1); PG8_BAR;
;             PG8_LDA(At, 1, 1); PG8_STAGE(PG8_SA(1, 0), a3, voffA);
;             PG8_BAR; PG8_WAIT_L(0); PG8_MMA(1, 0, At, B0); PG8_BAR; PG8_SCHED;
;             PG8_STAGE(PG8_SB(1, 1), b3 + hstepB, voffB);
.Lrs_skip:
	s_waitcnt vmcnt(8) lgkmcnt(0)
	s_barrier
	v_mfma_f32_16x16x32_bf16 v[124:127], v[130:133], v[146:149], v[124:127]
	v_mfma_f32_16x16x32_bf16 v[120:123], v[138:141], v[146:149], v[120:123]
	v_mfma_f32_16x16x32_bf16 v[112:115], v[130:133], v[154:157], v[112:115]
	v_mfma_f32_16x16x32_bf16 v[104:107], v[138:141], v[154:157], v[104:107]
	v_mfma_f32_16x16x32_bf16 v[96:99], v[130:133], v[162:165], v[96:99]
	v_mfma_f32_16x16x32_bf16 v[88:91], v[138:141], v[162:165], v[88:91]
	v_mfma_f32_16x16x32_bf16 v[80:83], v[130:133], v[194:197], v[80:83]
	v_mfma_f32_16x16x32_bf16 v[72:75], v[138:141], v[194:197], v[72:75]
	v_mfma_f32_16x16x32_bf16 v[124:127], v[134:137], v[150:153], v[124:127]
	v_mfma_f32_16x16x32_bf16 v[120:123], v[142:145], v[150:153], v[120:123]
	v_mfma_f32_16x16x32_bf16 v[112:115], v[134:137], v[158:161], v[112:115]
	v_mfma_f32_16x16x32_bf16 v[104:107], v[142:145], v[158:161], v[104:107]
	v_mfma_f32_16x16x32_bf16 v[96:99], v[134:137], v[190:193], v[96:99]
	v_mfma_f32_16x16x32_bf16 v[88:91], v[142:145], v[190:193], v[88:91]
	v_mfma_f32_16x16x32_bf16 v[80:83], v[134:137], v[198:201], v[80:83]
	v_mfma_f32_16x16x32_bf16 v[72:75], v[142:145], v[198:201], v[72:75]
	v_mfma_f32_16x16x32_bf16 v[116:119], v[202:205], v[146:149], v[116:119]
	v_mfma_f32_16x16x32_bf16 v[108:111], v[234:237], v[146:149], v[108:111]
	v_mfma_f32_16x16x32_bf16 v[100:103], v[202:205], v[154:157], v[100:103]
	v_mfma_f32_16x16x32_bf16 v[92:95], v[234:237], v[154:157], v[92:95]
	v_mfma_f32_16x16x32_bf16 v[84:87], v[202:205], v[162:165], v[84:87]
	v_mfma_f32_16x16x32_bf16 v[76:79], v[234:237], v[162:165], v[76:79]
	v_mfma_f32_16x16x32_bf16 v[68:71], v[202:205], v[194:197], v[68:71]
	v_mfma_f32_16x16x32_bf16 v[64:67], v[234:237], v[194:197], v[64:67]
	v_mfma_f32_16x16x32_bf16 v[116:119], v[230:233], v[150:153], v[116:119]
	v_mfma_f32_16x16x32_bf16 v[108:111], v[238:241], v[150:153], v[108:111]
	v_mfma_f32_16x16x32_bf16 v[100:103], v[230:233], v[158:161], v[100:103]
	v_mfma_f32_16x16x32_bf16 v[92:95], v[238:241], v[158:161], v[92:95]
	v_mfma_f32_16x16x32_bf16 v[84:87], v[230:233], v[190:193], v[84:87]
	v_mfma_f32_16x16x32_bf16 v[76:79], v[238:241], v[190:193], v[76:79]
	v_mfma_f32_16x16x32_bf16 v[68:71], v[230:233], v[198:201], v[68:71]
	v_mfma_f32_16x16x32_bf16 v[64:67], v[238:241], v[198:201], v[64:67]
	s_barrier
	ds_read_b128 v[146:149], v228 offset:49152
	ds_read_b128 v[150:153], v228 offset:50176
	ds_read_b128 v[154:157], v228 offset:51200
	ds_read_b128 v[158:161], v228 offset:52224
	ds_read_b128 v[162:165], v228 offset:53248
	ds_read_b128 v[190:193], v228 offset:54272
	ds_read_b128 v[194:197], v228 offset:55296
	ds_read_b128 v[198:201], v228 offset:56320
	s_add_i32 s44, s57, 0x18000
	v_lshl_add_u64 v[166:167], v[166:167], 0, s[88:89]
	s_mov_b32 m0, s44
	v_lshl_add_u64 v[206:207], v[206:207], 0, s[88:89]
	global_load_lds_dwordx4 v[166:167], off
	s_add_i32 m0, s44, 0x2000
	v_lshl_add_u64 v[242:243], v[242:243], 0, s[88:89]
	global_load_lds_dwordx4 v[206:207], off
	s_mov_b32 m0, s60
	v_lshl_add_u64 v[244:245], v[244:245], 0, s[88:89]
	global_load_lds_dwordx4 v[242:243], off
	s_mov_b32 m0, s61
	s_add_i32 s44, s57, 0x1c000
	v_lshl_add_u64 v[246:247], v[246:247], 0, s[88:89]
	global_load_lds_dwordx4 v[244:245], off
	s_mov_b32 m0, s44
	v_lshl_add_u64 v[248:249], v[248:249], 0, s[88:89]
	global_load_lds_dwordx4 v[246:247], off
	s_add_i32 m0, s44, 0x2000
	s_nop 0
	global_load_lds_dwordx4 v[248:249], off
	s_cmp_lt_u32 s35, s16
	s_cbranch_scc1 .Le0_skip
	s_cmp_eq_u32 s32, 0
	s_cbranch_scc1 .Le0_skip
;     __device__ __forceinline__ void operator()(const f32x4 (&acc)[2][2][4][2], const Unit& u, int wr, int wc, int fr, int fq, const LAS float* rsl) const {
;     ...
;                 const float rstd = rsqrtf(rs[ai][m] * (1.f / 1024.f) + EPS);
;                 bf16_t* rp = proj + (size_t)row * PW + wc * 32 + 8 * fq;
;                 if (pn < 9) {
; #pragma unroll
;                     for (int bj = 0; bj < 2; ++bj) store8bf_nt(rp + pn * 256 + bj * 128, acc[ai][bj][m][0] * rstd, acc[ai][bj][m][1] * rstd);
	v_add_u32_e32 v242, s34, v171
	v_mad_i64_i32 v[244:245], s[44:45], v242, s0, v[182:183]
	s_lshl_b32 s46, s48, 9
	s_mov_b32 s47, 0
	v_lshl_add_u64 v[244:245], v[244:245], 0, s[46:47]
	s_waitcnt lgkmcnt(0)
	v_pk_mul_f32 v[124:125], v[124:125], v[250:251] op_sel_hi:[1,0]
	v_pk_mul_f32 v[126:127], v[126:127], v[250:251] op_sel_hi:[1,0]
	v_pk_mul_f32 v[120:121], v[120:121], v[250:251] op_sel_hi:[1,0]
	v_pk_mul_f32 v[122:123], v[122:123], v[250:251] op_sel_hi:[1,0]
	v_cvt_pk_bf16_f32 v124, v124, v125
	v_cvt_pk_bf16_f32 v125, v126, v127
	v_cvt_pk_bf16_f32 v126, v120, v121
	v_cvt_pk_bf16_f32 v127, v122, v123
	global_store_dwordx4 v[244:245], v[124:127], off nt
	v_pk_mul_f32 v[116:117], v[116:117], v[250:251] op_sel_hi:[1,0]
	v_pk_mul_f32 v[118:119], v[118:119], v[250:251] op_sel_hi:[1,0]
	v_pk_mul_f32 v[108:109], v[108:109], v[250:251] op_sel_hi:[1,0]
	v_pk_mul_f32 v[110:111], v[110:111], v[250:251] op_sel_hi:[1,0]
	v_cvt_pk_bf16_f32 v116, v116, v117
	v_cvt_pk_bf16_f32 v117, v118, v119
	v_cvt_pk_bf16_f32 v118, v108, v109
	v_cvt_pk_bf16_f32 v119, v110, v111
	global_store_dwordx4 v[244:245], v[116:119], off offset:256 nt
	v_add_co_u32_e32 v244, vcc, 0x22000, v244
	s_nop 1
	v_addc_co_u32_e32 v245, vcc, 0, v245, vcc
	v_pk_mul_f32 v[112:113], v[112:113], v[250:251] op_sel:[0,1] op_sel_hi:[1,1]
	v_pk_mul_f32 v[114:115], v[114:115], v[250:251] op_sel:[0,1] op_sel_hi:[1,1]
	v_pk_mul_f32 v[104:105], v[104:105], v[250:251] op_sel:[0,1] op_sel_hi:[1,1]
	v_pk_mul_f32 v[106:107], v[106:107], v[250:251] op_sel:[0,1] op_sel_hi:[1,1]
	v_cvt_pk_bf16_f32 v112, v112, v113
	v_cvt_pk_bf16_f32 v113, v114, v115
	v_cvt_pk_bf16_f32 v114, v104, v105
	v_cvt_pk_bf16_f32 v115, v106, v107
	global_store_dwordx4 v[244:245], v[112:115], off nt
	v_pk_mul_f32 v[100:101], v[100:101], v[250:251] op_sel:[0,1] op_sel_hi:[1,1]
	v_pk_mul_f32 v[102:103], v[102:103], v[250:251] op_sel:[0,1] op_sel_hi:[1,1]
	v_pk_mul_f32 v[92:93], v[92:93], v[250:251] op_sel:[0,1] op_sel_hi:[1,1]
	v_pk_mul_f32 v[94:95], v[94:95], v[250:251] op_sel:[0,1] op_sel_hi:[1,1]
	v_cvt_pk_bf16_f32 v100, v100, v101
	v_cvt_pk_bf16_f32 v101, v102, v103
	v_cvt_pk_bf16_f32 v102, v92, v93
	v_cvt_pk_bf16_f32 v103, v94, v95
	global_store_dwordx4 v[244:245], v[100:103], off offset:256 nt
	v_add_co_u32_e32 v244, vcc, 0x22000, v244
	s_nop 1
	v_addc_co_u32_e32 v245, vcc, 0, v245, vcc
	v_pk_mul_f32 v[96:97], v[96:97], v[252:253] op_sel_hi:[1,0]
	v_pk_mul_f32 v[98:99], v[98:99], v[252:253] op_sel_hi:[1,0]
	v_pk_mul_f32 v[88:89], v[88:89], v[252:253] op_sel_hi:[1,0]
	v_pk_mul_f32 v[90:91], v[90:91], v[252:253] op_sel_hi:[1,0]
	v_cvt_pk_bf16_f32 v96, v96, v97
	v_cvt_pk_bf16_f32 v97, v98, v99
	v_cvt_pk_bf16_f32 v98, v88, v89
	v_cvt_pk_bf16_f32 v99, v90, v91
	global_store_dwordx4 v[244:245], v[96:99], off nt
	v_pk_mul_f32 v[84:85], v[84:85], v[252:253] op_sel_hi:[1,0]
	v_pk_mul_f32 v[86:87], v[86:87], v[252:253] op_sel_hi:[1,0]
	v_pk_mul_f32 v[76:77], v[76:77], v[252:253] op_sel_hi:[1,0]
	v_pk_mul_f32 v[78:79], v[78:79], v[252:253] op_sel_hi:[1,0]
	v_cvt_pk_bf16_f32 v84, v84, v85
	v_cvt_pk_bf16_f32 v85, v86, v87
	v_cvt_pk_bf16_f32 v86, v76, v77
	v_cvt_pk_bf16_f32 v87, v78, v79
	global_store_dwordx4 v[244:245], v[84:87], off offset:256 nt
	v_add_co_u32_e32 v244, vcc, 0x22000, v244
	s_nop 1
	v_addc_co_u32_e32 v245, vcc, 0, v245, vcc
	v_pk_mul_f32 v[80:81], v[80:81], v[252:253] op_sel:[0,1] op_sel_hi:[1,1]
	v_pk_mul_f32 v[82:83], v[82:83], v[252:253] op_sel:[0,1] op_sel_hi:[1,1]
	v_pk_mul_f32 v[72:73], v[72:73], v[252:253] op_sel:[0,1] op_sel_hi:[1,1]
	v_pk_mul_f32 v[74:75], v[74:75], v[252:253] op_sel:[0,1] op_sel_hi:[1,1]
	v_cvt_pk_bf16_f32 v80, v80, v81
	v_cvt_pk_bf16_f32 v81, v82, v83
	v_cvt_pk_bf16_f32 v82, v72, v73
	v_cvt_pk_bf16_f32 v83, v74, v75
	global_store_dwordx4 v[244:245], v[80:83], off nt
	v_pk_mul_f32 v[68:69], v[68:69], v[252:253] op_sel:[0,1] op_sel_hi:[1,1]
	v_pk_mul_f32 v[70:71], v[70:71], v[252:253] op_sel:[0,1] op_sel_hi:[1,1]
	v_pk_mul_f32 v[64:65], v[64:65], v[252:253] op_sel:[0,1] op_sel_hi:[1,1]
	v_pk_mul_f32 v[66:67], v[66:67], v[252:253] op_sel:[0,1] op_sel_hi:[1,1]
	v_cvt_pk_bf16_f32 v68, v68, v69
	v_cvt_pk_bf16_f32 v69, v70, v71
	v_cvt_pk_bf16_f32 v70, v64, v65
	v_cvt_pk_bf16_f32 v71, v66, v67
	global_store_dwordx4 v[244:245], v[68:71], off offset:256 nt
	s_waitcnt vmcnt(16) lgkmcnt(0)
	s_barrier
	s_branch .Le0_join
